# ctx FFN down-proj split-K: 128 scattered f32 atomics/lane replaced by 32 plain 16B stores of partial sums (staged in d_out) folded in order by the ctx pre-norm; ctx pre-norm moved to WGs with a spare
# speedup vs baseline: 1.0744x; 1.0744x over previous
; #define PG8_STAGE(bufoff, gbase, voff) do { _Pragma("unroll") for (int _i = 0; _i < 2; ++_i) \
;         __builtin_amdgcn_global_load_lds((const unsigned*)((const char*)(gbase) + (voff)[_i]), (LAS unsigned*)(lds + (bufoff) + ldsw + _i * 8192), 16, 0, 0); } while (0)
; #define PG8_WAIT_V(n) asm volatile("s_waitcnt vmcnt(" #n ")" ::: "memory")
; #define PG8_BAR __builtin_amdgcn_s_barrier()
; template <class Epi, class Sched>
; __device__ __forceinline__ void gemm_phase(LAS unsigned char* lds, const Gemm g, const Sched& S, const Epi& E) {
;     ...
;     for (int i = 0; i < 2; ++i) { int R, C; stage_rc(tid * 16 + i * 8192, R, C); const int Rb = Epi::PERM ? ((R & ~31) + perm32(R & 31)) : R;
;         voffA[i] = (unsigned)(R * g.lda + C) * 2u; voffB[i] = (unsigned)(Rb * g.ldb + C) * 2u; }
;     const size_t kstep = (size_t)(BK * 2);
;     const size_t hstepA = (size_t)HALF * g.lda * 2, hstepB = (size_t)HALF * g.ldb * 2;
;     const unsigned ldsw = (unsigned)wid * 1024u;
;     const int aoff = lds_byte(wr * 64 + fr, fq * 8), boff = lds_byte(wc * 32 + fr, fq * 8);
;     ...
;     Unit cur, nxt; int ui = 0;
;     if (!S.next(0, cur)) return;
;     f32x4 acc[2][2][4][2];
; #pragma unroll
;     for (int a = 0; a < 2; ++a)
; #pragma unroll
;         for (int b = 0; b < 2; ++b)
; #pragma unroll
;             for (int m = 0; m < 4; ++m)
; #pragma unroll
;                 for (int n = 0; n < 2; ++n) acc[a][b][m][n] = (f32x4){0.f, 0.f, 0.f, 0.f};
;     bf16x8 At[4][2], B0[2][2], B1[2][2];
;     const char* cA = cur.A; const char* cB = cur.B;
;     PG8_STAGE(PG8_SB(0, 0), cB, voffB); PG8_STAGE(PG8_SB(0, 1), cB + hstepB, voffB); PG8_STAGE(PG8_SA(0, 0), cA, voffA); PG8_STAGE(PG8_SA(0, 1), cA + hstepA, voffA);
;     if (wr == 1) PG8_BAR;
;     PG8_WAIT_V(2); PG8_BAR;
;     PG8_STAGE(PG8_SB(1, 0), cB + kstep, voffB); PG8_STAGE(PG8_SA(1, 0), cA + kstep, voffA); PG8_STAGE(PG8_SB(1, 1), cB + hstepB + kstep, voffB);
;     PG8_WAIT_V(6); PG8_BAR;
;     __device__ __forceinline__ bool next(int i, Unit& u) const {
;     ...
;         const int t = L / 11, sp = L - t * 11, pm = t >> 2, pn = t & 3;
;         u.pm = pm; u.pn = pn; u.z = sp; u.A = A + ((size_t)(NTOK + pm * 256) * DFF + sp * 256) * 2; u.B = B + ((size_t)(pn * 256) * DFF + sp * 256) * 2; return true;
.LBB0_333:
	v_mov_b32_e32 v9, v176
	s_movk_i32 s1, 0x100
	v_readfirstlane_b32 s0, v9
	s_cmpk_gt_i32 s84, 0xaf
	s_cbranch_scc1 .LBB0_350
	v_lshlrev_b32_e32 v0, 4, v9
	s_waitcnt lgkmcnt(0)
	v_add_u32_e32 v1, 0x2000, v0
	v_ashrrev_i32_e32 v2, 31, v1
	v_lshrrev_b32_e32 v2, 22, v2
	v_add_u32_e32 v2, v1, v2
	v_ashrrev_i32_e32 v8, 10, v2
	v_mul_i32_i24_e32 v2, 0x400, v8
	v_sub_u32_e32 v1, v1, v2
	v_lshrrev_b32_e32 v2, 4, v1
	v_bitop3_b32 v1, v2, v1, 32 bitop3:0x6c
	v_ashrrev_i32_e32 v2, 31, v1
	v_lshrrev_b32_e32 v2, 26, v2
	v_add_u32_e32 v2, v1, v2
	v_ashrrev_i32_e32 v10, 6, v2
	v_and_b32_e32 v2, 0xc0, v2
	s_mul_hi_i32 s12, s84, 0x2e8ba2e9
	v_sub_u32_e32 v1, v1, v2
	v_mov_b32_e32 v2, 1
	s_lshr_b32 s13, s12, 31
	s_ashr_i32 s12, s12, 1
	v_ashrrev_i16_sdwa v1, v2, sext(v1) dst_sel:DWORD dst_unused:UNUSED_PAD src0_sel:DWORD src1_sel:BYTE_0
	s_add_i32 s12, s12, s13
	v_lshlrev_b32_e32 v3, 3, v8
	s_waitcnt vmcnt(1)
	v_bfe_i32 v12, v1, 0, 16
	v_bfe_i32 v1, v9, 27, 1
	s_mul_i32 s13, s12, -11
	s_ashr_i32 s57, s12, 2
	v_and_b32_e32 v3, 0xfffff0, v3
	v_lshrrev_b32_e32 v1, 22, v1
	s_add_i32 s13, s13, s84
	s_lshl_b32 s64, s13, 22
	s_add_u32 s64, s78, s64
	s_addc_u32 s65, s79, 0
	s_and_b32 s58, s12, 3
	s_lshl_b32 s12, s57, 8
	s_ashr_i32 s16, s0, 6
	v_add_u32_e32 v3, v10, v3
	s_movk_i32 s20, 0xb00
	v_lshlrev_b32_e32 v4, 5, v8
	v_add_u32_e32 v1, v0, v1
	s_addk_i32 s12, 0x4000
	s_lshl_b32 s15, s13, 8
	s_ashr_i32 s18, s0, 8
	s_lshl_b32 s40, s16, 10
	v_mul_lo_u32 v3, v3, s20
	v_and_b32_e32 v11, 32, v4
	v_and_b32_e32 v1, 0xfffffc00, v1
	s_mul_hi_i32 s14, s12, 0xb00
	s_mulk_i32 s12, 0xb00
	s_ashr_i32 s17, s15, 31
	v_or_b32_e32 v3, v3, v11
	v_sub_u32_e32 v0, v0, v1
	s_add_u32 s12, s12, s15
	v_add_lshl_u32 v128, v3, v12, 1
	v_lshrrev_b32_e32 v1, 4, v0
	v_ashrrev_i32_e32 v3, 31, v9
	s_addc_u32 s13, s14, s17
	v_bitop3_b32 v0, v1, v0, 32 bitop3:0x6c
	v_lshrrev_b32_e32 v3, 26, v3
	s_lshl_b64 s[12:13], s[12:13], 1
	v_ashrrev_i32_e32 v1, 31, v0
	v_add_u32_e32 v3, v9, v3
	s_add_u32 s30, s92, s12
	v_lshrrev_b32_e32 v1, 26, v1
	v_ashrrev_i32_e32 v14, 6, v3
	s_addc_u32 s31, s93, s13
	s_mul_i32 s12, s58, 0xb0000
	v_add_u32_e32 v1, v0, v1
	v_lshlrev_b32_e32 v3, 3, v14
	s_add_u32 s12, s15, s12
	v_ashrrev_i32_e32 v13, 6, v1
	v_and_b32_e32 v3, 0xfffff0, v3
	v_and_b32_e32 v1, 0xc0, v1
	s_addc_u32 s13, s17, 0
	v_add_u32_e32 v3, v13, v3
	v_lshlrev_b32_e32 v4, 5, v14
	v_sub_u32_e32 v0, v0, v1
	s_lshl_b64 s[12:13], s[12:13], 1
	v_mul_lo_u32 v3, v3, s20
	v_and_b32_e32 v15, 32, v4
	v_ashrrev_i16_sdwa v0, v2, sext(v0) dst_sel:DWORD dst_unused:UNUSED_PAD src0_sel:DWORD src1_sel:BYTE_0
	s_add_u32 s34, s33, s12
	v_or_b32_e32 v3, v3, v15
	v_bfe_i32 v16, v0, 0, 16
	s_addc_u32 s35, s46, s13
	s_add_i32 s41, s40, 0
	v_add_lshl_u32 v130, v3, v16, 1
	s_add_i32 m0, s41, 0x10000
	v_mov_b32_e32 v131, 0
	global_load_lds_dwordx4 v130, s[34:35]
	s_add_i32 m0, s41, 0x12000
	s_add_u32 s12, s34, 0xb0000
	global_load_lds_dwordx4 v128, s[34:35]
	s_addc_u32 s13, s35, 0
	s_add_i32 m0, s41, 0x14000
	s_add_i32 s42, s41, 0x2000
	global_load_lds_dwordx4 v130, s[12:13]
	s_add_i32 m0, s41, 0x16000
	v_mov_b32_e32 v129, v131
	global_load_lds_dwordx4 v128, s[12:13]
	s_mov_b32 m0, s41
	s_add_u32 s12, s30, 0xb0000
	global_load_lds_dwordx4 v130, s[30:31]
	s_mov_b32 m0, s42
	s_addc_u32 s13, s31, 0
	s_add_i32 s43, s41, 0x4000
	global_load_lds_dwordx4 v128, s[30:31]
	s_mov_b32 m0, s43
	s_add_i32 s44, s41, 0x6000
	global_load_lds_dwordx4 v130, s[12:13]
	s_mov_b32 m0, s44
	s_cmp_eq_u32 s18, 1
	global_load_lds_dwordx4 v128, s[12:13]
	s_mov_b32 s45, 0
	v_lshl_add_u64 v[6:7], s[34:35], 0, v[130:131]
	v_lshl_add_u64 v[4:5], s[34:35], 0, v[128:129]
	v_lshl_add_u64 v[0:1], s[30:31], 0, v[130:131]
	s_cselect_b64 s[12:13], -1, 0
	s_cmp_lg_u32 s18, 1
	v_lshl_add_u64 v[2:3], s[30:31], 0, v[128:129]
	s_cbranch_scc1 .LBB0_336
	s_barrier

; template <class Epi, class Sched>
; __device__ __forceinline__ void gemm_phase(LAS unsigned char* lds, const Gemm g, const Sched& S, const Epi& E) {
;     ...
;         const bool has_next = S.next(ui + 1, nxt);
;         const char* nA = has_next ? nxt.A : cA; const char* nB = has_next ? nxt.B : cB;
;         for (int t = 0; t < nt; t += 2) {
;             const bool last = (t == nt - 2);
;             const char* a1 = cA + (size_t)(t + 1) * kstep;
;             const char* a2 = last ? nA : cA + (size_t)(t + 2) * kstep; const char* b2 = last ? nB : cB + (size_t)(t + 2) * kstep;
;             const char* a3 = a2 + kstep; const char* b3 = b2 + kstep;
;             PG8_LDB(B0, 0, 0); PG8_LDB(B1, 0, 1); PG8_SCHED; PG8_LDA(At, 0, 0); PG8_STAGE(PG8_SA(1, 1), a1 + hstepA, voffA);
;             PG8_WAIT_V(8); PG8_WAIT_L(0); PG8_BAR; PG8_MMA(0, 0, At, B0); PG8_MMA(0, 1, At, B1); PG8_BAR; PG8_SCHED;
;             PG8_LDA(At, 0, 1); PG8_STAGE(PG8_SB(0, 0), b2, voffB); PG8_STAGE(PG8_SB(0, 1), b2 + hstepB, voffB); PG8_STAGE(PG8_SA(0, 0), a2, voffA);
;             PG8_WAIT_V(8); PG8_WAIT_L(0); PG8_BAR; PG8_MMA(1, 0, At, B0); PG8_MMA(1, 1, At, B1); PG8_BAR; PG8_SCHED;
;             PG8_LDB(B0, 1, 0); PG8_LDB(B1, 1, 1); PG8_SCHED; PG8_LDA(At, 1, 0); PG8_STAGE(PG8_SA(0, 1), a2 + hstepA, voffA);
;             PG8_WAIT_V(8); PG8_WAIT_L(0); PG8_BAR; PG8_MMA(0, 0, At, B0); PG8_MMA(0, 1, At, B1); PG8_BAR; PG8_SCHED;
;             PG8_LDA(At, 1, 1); PG8_STAGE(PG8_SB(1, 0), b3, voffB); PG8_STAGE(PG8_SB(1, 1), b3 + hstepB, voffB); PG8_STAGE(PG8_SA(1, 0), a3, voffA);
;             PG8_WAIT_V(8); PG8_WAIT_L(0); PG8_BAR; PG8_MMA(1, 0, At, B0); PG8_MMA(1, 1, At, B1); PG8_BAR; PG8_SCHED;
;         }
;         if constexpr (ALIGN_EPI) { if (wr == 0) PG8_BAR; }
;         if constexpr (!Epi::AFTER_DRAIN) E(acc, cur, wr, wc, fr, fq);
;         if (!has_next) break;
; #pragma unroll
;         for (int a = 0; a < 2; ++a)
; #pragma unroll
;             for (int b = 0; b < 2; ++b)
; #pragma unroll
;                 for (int m = 0; m < 4; ++m)
; #pragma unroll
;                     for (int n = 0; n < 2; ++n) acc[a][b][m][n] = (f32x4){0.f, 0.f, 0.f, 0.f};
;         cur = nxt; cA = nA; cB = nB; ++ui;
;     __device__ __forceinline__ bool next(int i, Unit& u) const {
;         const int L = i * G + c; if (L >= 176) return false;
;         const int t = L / 11, sp = L - t * 11, pm = t >> 2, pn = t & 3;
.LBB0_338:
	s_andn2_b64 vcc, exec, s[26:27]
	s_mov_b64 s[64:65], s[100:101]
	s_mov_b32 s58, s55
	s_mov_b32 s57, s56
	s_mov_b64 s[34:35], s[24:25]
	s_mov_b64 s[30:31], s[22:23]
	s_cbranch_vccz .LBB0_349
.LBB0_339:
	s_add_i32 s45, s45, 1
	s_mul_i32 s36, s45, s82
	s_add_i32 s36, s36, s84
	s_cmpk_lt_i32 s36, 0xb0
	s_cselect_b64 s[26:27], -1, 0
	s_cmpk_gt_i32 s36, 0xaf
	s_cbranch_scc1 .LBB0_341
	s_mul_hi_i32 s22, s36, 0x2e8ba2e9
	s_lshr_b32 s23, s22, 31
	s_ashr_i32 s22, s22, 1
	s_add_i32 s22, s22, s23
	s_mul_i32 s23, s22, -11
	s_ashr_i32 s56, s22, 2
	s_add_i32 s23, s23, s36
	s_lshl_b32 s100, s23, 22
	s_add_u32 s100, s78, s100
	s_addc_u32 s101, s79, 0
	s_and_b32 s55, s22, 3
	s_lshl_b32 s22, s56, 8
	s_addk_i32 s22, 0x4000
	s_lshl_b32 s25, s23, 8
	s_mul_hi_i32 s24, s22, 0xb00
	s_mulk_i32 s22, 0xb00
	s_ashr_i32 s36, s25, 31
	s_add_u32 s22, s22, s25
	s_addc_u32 s23, s24, s36
	s_lshl_b64 s[22:23], s[22:23], 1
	s_add_u32 s22, s92, s22
	s_addc_u32 s23, s93, s23
	s_mul_i32 s24, s55, 0xb0000
	s_add_u32 s24, s25, s24
	s_addc_u32 s25, s36, 0
	s_lshl_b64 s[24:25], s[24:25], 1
	s_add_u32 s24, s33, s24
	s_addc_u32 s25, s46, s25

;     __device__ __forceinline__ void operator()(const f32x4 (&acc)[2][2][4][2], const Unit& u, int wr, int wc, int fr, int fq) const {
;         const int row0 = u.pm * 256 + wr * 64 + fr, col0 = u.pn * 256 + wc * 32 + 4 * fq;
; #pragma unroll
;         for (int bj = 0; bj < 2; ++bj)
; #pragma unroll
;             for (int n = 0; n < 2; ++n) { const f32x4 gv = *(const f32x4*)(gate + col0 + bj * 128 + n * 16) * gmul;
; #pragma unroll
;                 for (int ai = 0; ai < 2; ++ai)
; #pragma unroll
;                     for (int m = 0; m < 4; ++m) { float* o = H + (size_t)(row0 + ai * 128 + m * 16) * D + col0 + bj * 128 + n * 16; const f32x4 v = gv * acc[ai][bj][m][n];
; #pragma unroll
;                         for (int i = 0; i < 4; ++i) unsafeAtomicAdd(o + i, v[i]); } }
.LBB0_346:
	v_lshl_or_b32 v136, s58, 8, v156
	v_ashrrev_i32_e32 v137, 31, v136
	v_lshlrev_b64 v[138:139], 2, v[136:137]
	v_lshl_add_u64 v[136:137], s[14:15], 0, v[138:139]
	global_load_dwordx4 v[160:163], v[136:137], off
	v_lshl_add_u32 v140, s57, 8, v154
	v_ashrrev_i32_e32 v141, 31, v140
	v_or_b32_e32 v142, 16, v140
	v_or_b32_e32 v144, 32, v140
	v_or_b32_e32 v146, 48, v140
	v_lshlrev_b64 v[140:141], 12, v[140:141]
	v_lshl_add_u64 v[140:141], s[64:65], 0, v[140:141]
	s_mov_b32 s38, 0x80000
	v_lshl_add_u64 v[150:151], v[140:141], 0, v[138:139]
	v_add_co_u32_e32 v164, vcc, s38, v150
	v_ashrrev_i32_e32 v143, 31, v142
	s_nop 0
	v_addc_co_u32_e32 v165, vcc, 0, v151, vcc
	v_add_co_u32_e32 v166, vcc, s53, v150
	v_ashrrev_i32_e32 v145, 31, v144
	s_nop 0
	v_addc_co_u32_e32 v167, vcc, 0, v151, vcc
	v_ashrrev_i32_e32 v147, 31, v146
	v_add_co_u32_e32 v168, vcc, s54, v150
	s_mov_b32 s39, 0xb0000
	v_lshlrev_b64 v[142:143], 12, v[142:143]
	v_lshlrev_b64 v[144:145], 12, v[144:145]
	v_lshlrev_b64 v[146:147], 12, v[146:147]
	v_addc_co_u32_e32 v169, vcc, 0, v151, vcc
	s_mov_b64 s[30:31], 0x80000
	s_mov_b64 s[34:35], 0x90000
	s_mov_b64 s[36:37], 0xb0000
	v_lshl_add_u64 v[140:141], s[64:65], 0, v[142:143]
	v_lshl_add_u64 v[142:143], s[64:65], 0, v[144:145]
	v_lshl_add_u64 v[144:145], s[64:65], 0, v[146:147]
	v_add_co_u32_e32 v170, vcc, s39, v150
	v_lshl_add_u64 v[152:153], v[140:141], 0, v[138:139]
	v_lshl_add_u64 v[148:149], v[142:143], 0, v[138:139]
	v_lshl_add_u64 v[146:147], v[144:145], 0, v[138:139]
	v_lshl_add_u64 v[144:145], v[150:151], 0, s[30:31]
	v_lshl_add_u64 v[142:143], v[150:151], 0, s[34:35]
	v_lshl_add_u64 v[140:141], v[150:151], 0, s[20:21]
	v_lshl_add_u64 v[138:139], v[150:151], 0, s[36:37]
	v_addc_co_u32_e32 v171, vcc, 0, v151, vcc
	s_andn2_b64 vcc, exec, s[26:27]
	s_mov_b64 s[26:27], -1
	s_waitcnt vmcnt(0)
	v_mul_f32_e32 v160, 0.5, v160
	v_mul_f32_e32 v161, 0.5, v161
	v_mul_f32_e32 v162, 0.5, v162
	v_mul_f32_e32 v163, 0.5, v163
	v_mul_f32_e32 v124, v124, v160
	v_mul_f32_e32 v125, v125, v161
	v_mul_f32_e32 v126, v126, v162
	v_mul_f32_e32 v127, v127, v163
	v_mul_f32_e32 v120, v120, v160
	v_mul_f32_e32 v121, v121, v161
	v_mul_f32_e32 v122, v122, v162
	v_mul_f32_e32 v123, v123, v163
	v_mul_f32_e32 v116, v116, v160
	v_mul_f32_e32 v117, v117, v161
	v_mul_f32_e32 v118, v118, v162
	v_mul_f32_e32 v119, v119, v163
	v_mul_f32_e32 v112, v112, v160
	v_mul_f32_e32 v113, v113, v161
	v_mul_f32_e32 v114, v114, v162
	v_mul_f32_e32 v115, v115, v163
	v_mul_f32_e32 v108, v108, v160
	v_mul_f32_e32 v109, v109, v161
	v_mul_f32_e32 v110, v110, v162
	v_mul_f32_e32 v111, v111, v163
	v_mul_f32_e32 v104, v104, v160
	v_mul_f32_e32 v105, v105, v161
	v_mul_f32_e32 v106, v106, v162
	v_mul_f32_e32 v107, v107, v163
	v_mul_f32_e32 v100, v100, v160
	v_mul_f32_e32 v101, v101, v161
	v_mul_f32_e32 v102, v102, v162
	v_mul_f32_e32 v103, v103, v163
	v_mul_f32_e32 v96, v96, v160
	v_mul_f32_e32 v97, v97, v161
	v_mul_f32_e32 v98, v98, v162
	v_mul_f32_e32 v99, v99, v163
	global_store_dwordx4 v[150:151], v[124:127], off
	global_store_dwordx4 v[152:153], v[120:123], off
	global_store_dwordx4 v[148:149], v[116:119], off
	global_store_dwordx4 v[146:147], v[112:115], off
	global_store_dwordx4 v[144:145], v[108:111], off
	global_store_dwordx4 v[142:143], v[104:107], off
	global_store_dwordx4 v[140:141], v[100:103], off
	global_store_dwordx4 v[138:139], v[96:99], off
	global_load_dwordx4 v[96:99], v[136:137], off offset:64
	s_waitcnt vmcnt(0)
;     __device__ __forceinline__ void operator()(const f32x4 (&acc)[2][2][4][2], const Unit& u, int wr, int wc, int fr, int fq) const {
;         const int row0 = u.pm * 256 + wr * 64 + fr, col0 = u.pn * 256 + wc * 32 + 4 * fq;
; #pragma unroll
;         for (int bj = 0; bj < 2; ++bj)
; #pragma unroll
;             for (int n = 0; n < 2; ++n) { const f32x4 gv = *(const f32x4*)(gate + col0 + bj * 128 + n * 16) * gmul;
; #pragma unroll
;                 for (int ai = 0; ai < 2; ++ai)
; #pragma unroll
;                     for (int m = 0; m < 4; ++m) { float* o = H + (size_t)(row0 + ai * 128 + m * 16) * D + col0 + bj * 128 + n * 16; const f32x4 v = gv * acc[ai][bj][m][n];
; #pragma unroll
;                         for (int i = 0; i < 4; ++i) unsafeAtomicAdd(o + i, v[i]); } }
	v_mul_f32_e32 v96, 0.5, v96
	v_mul_f32_e32 v97, 0.5, v97
	v_mul_f32_e32 v98, 0.5, v98
	v_mul_f32_e32 v99, 0.5, v99
	v_mul_f32_e32 v92, v92, v96
	v_mul_f32_e32 v93, v93, v97
	v_mul_f32_e32 v94, v94, v98
	v_mul_f32_e32 v95, v95, v99
	v_mul_f32_e32 v88, v88, v96
	v_mul_f32_e32 v89, v89, v97
	v_mul_f32_e32 v90, v90, v98
	v_mul_f32_e32 v91, v91, v99
	v_mul_f32_e32 v84, v84, v96
	v_mul_f32_e32 v85, v85, v97
	v_mul_f32_e32 v86, v86, v98
	v_mul_f32_e32 v87, v87, v99
	v_mul_f32_e32 v80, v80, v96
	v_mul_f32_e32 v81, v81, v97
	v_mul_f32_e32 v82, v82, v98
	v_mul_f32_e32 v83, v83, v99
	v_mul_f32_e32 v76, v76, v96
	v_mul_f32_e32 v77, v77, v97
	v_mul_f32_e32 v78, v78, v98
	v_mul_f32_e32 v79, v79, v99
	v_mul_f32_e32 v72, v72, v96
	v_mul_f32_e32 v73, v73, v97
	v_mul_f32_e32 v74, v74, v98
	v_mul_f32_e32 v75, v75, v99
	v_mul_f32_e32 v68, v68, v96
	v_mul_f32_e32 v69, v69, v97
	v_mul_f32_e32 v70, v70, v98
	v_mul_f32_e32 v71, v71, v99
	v_mul_f32_e32 v64, v64, v96
	v_mul_f32_e32 v65, v65, v97
	v_mul_f32_e32 v66, v66, v98
	v_mul_f32_e32 v67, v67, v99
	global_store_dwordx4 v[150:151], v[92:95], off offset:64
	global_store_dwordx4 v[152:153], v[88:91], off offset:64
	global_store_dwordx4 v[148:149], v[84:87], off offset:64
	global_store_dwordx4 v[146:147], v[80:83], off offset:64
	global_store_dwordx4 v[144:145], v[76:79], off offset:64
	global_store_dwordx4 v[142:143], v[72:75], off offset:64
	global_store_dwordx4 v[140:141], v[68:71], off offset:64
	global_store_dwordx4 v[138:139], v[64:67], off offset:64
	global_load_dwordx4 v[64:67], v[136:137], off offset:512
	s_waitcnt vmcnt(0)
	v_mul_f32_e32 v64, 0.5, v64
	v_mul_f32_e32 v65, 0.5, v65
	v_mul_f32_e32 v66, 0.5, v66
	v_mul_f32_e32 v67, 0.5, v67
	v_mul_f32_e32 v60, v60, v64
	v_mul_f32_e32 v61, v61, v65
	v_mul_f32_e32 v62, v62, v66
	v_mul_f32_e32 v63, v63, v67
	v_mul_f32_e32 v56, v56, v64
	v_mul_f32_e32 v57, v57, v65
	v_mul_f32_e32 v58, v58, v66
	v_mul_f32_e32 v59, v59, v67
	v_mul_f32_e32 v52, v52, v64
	v_mul_f32_e32 v53, v53, v65
	v_mul_f32_e32 v54, v54, v66
	v_mul_f32_e32 v55, v55, v67
	v_mul_f32_e32 v48, v48, v64
	v_mul_f32_e32 v49, v49, v65
	v_mul_f32_e32 v50, v50, v66
	v_mul_f32_e32 v51, v51, v67
	v_mul_f32_e32 v44, v44, v64
	v_mul_f32_e32 v45, v45, v65
	v_mul_f32_e32 v46, v46, v66
	v_mul_f32_e32 v47, v47, v67
	v_mul_f32_e32 v40, v40, v64
	v_mul_f32_e32 v41, v41, v65
	v_mul_f32_e32 v42, v42, v66
	v_mul_f32_e32 v43, v43, v67
	v_mul_f32_e32 v36, v36, v64
	v_mul_f32_e32 v37, v37, v65
	v_mul_f32_e32 v38, v38, v66
	v_mul_f32_e32 v39, v39, v67
	v_mul_f32_e32 v32, v32, v64
	v_mul_f32_e32 v33, v33, v65
	v_mul_f32_e32 v34, v34, v66
	v_mul_f32_e32 v35, v35, v67
	global_store_dwordx4 v[150:151], v[60:63], off offset:512
	global_store_dwordx4 v[152:153], v[56:59], off offset:512
	global_store_dwordx4 v[148:149], v[52:55], off offset:512
	global_store_dwordx4 v[146:147], v[48:51], off offset:512
	global_store_dwordx4 v[144:145], v[44:47], off offset:512
	global_store_dwordx4 v[142:143], v[40:43], off offset:512
	global_store_dwordx4 v[140:141], v[36:39], off offset:512
	global_store_dwordx4 v[138:139], v[32:35], off offset:512
	global_load_dwordx4 v[32:35], v[136:137], off offset:576
	s_waitcnt vmcnt(0)
	v_mul_f32_e32 v32, 0.5, v32
	v_mul_f32_e32 v33, 0.5, v33
	v_mul_f32_e32 v34, 0.5, v34
	v_mul_f32_e32 v35, 0.5, v35
	v_mul_f32_e32 v28, v28, v32
	v_mul_f32_e32 v29, v29, v33
	v_mul_f32_e32 v30, v30, v34
	v_mul_f32_e32 v31, v31, v35
	v_mul_f32_e32 v24, v24, v32
	v_mul_f32_e32 v25, v25, v33
	v_mul_f32_e32 v26, v26, v34
	v_mul_f32_e32 v27, v27, v35
	v_mul_f32_e32 v20, v20, v32
	v_mul_f32_e32 v21, v21, v33
	v_mul_f32_e32 v22, v22, v34
	v_mul_f32_e32 v23, v23, v35
	v_mul_f32_e32 v16, v16, v32
	v_mul_f32_e32 v17, v17, v33
	v_mul_f32_e32 v18, v18, v34
	v_mul_f32_e32 v19, v19, v35
	v_mul_f32_e32 v12, v12, v32
	v_mul_f32_e32 v13, v13, v33
	v_mul_f32_e32 v14, v14, v34
	v_mul_f32_e32 v15, v15, v35
	v_mul_f32_e32 v8, v8, v32
	v_mul_f32_e32 v9, v9, v33
	v_mul_f32_e32 v10, v10, v34
	v_mul_f32_e32 v11, v11, v35
	v_mul_f32_e32 v4, v4, v32
	v_mul_f32_e32 v5, v5, v33
	v_mul_f32_e32 v6, v6, v34
	v_mul_f32_e32 v7, v7, v35
	v_mul_f32_e32 v0, v0, v32
	v_mul_f32_e32 v1, v1, v33
	v_mul_f32_e32 v2, v2, v34
	global_store_dwordx4 v[150:151], v[28:31], off offset:576
	global_store_dwordx4 v[152:153], v[24:27], off offset:576
	global_store_dwordx4 v[148:149], v[20:23], off offset:576
	global_store_dwordx4 v[146:147], v[16:19], off offset:576
	global_store_dwordx4 v[144:145], v[12:15], off offset:576
	global_store_dwordx4 v[142:143], v[8:11], off offset:576
	global_store_dwordx4 v[140:141], v[4:7], off offset:576
	v_mul_f32_e32 v3, v3, v35
	global_store_dwordx4 v[138:139], v[0:3], off offset:576
	s_cbranch_vccnz .LBB0_338
	s_andn2_b64 vcc, exec, s[12:13]
	s_cbranch_vccnz .LBB0_337
	s_barrier
	s_branch .LBB0_337

; __device__ __forceinline__ void prenorm_rows(const float* src0, const float* src1, int row_lo, int row_hi, const float* g, const float* scale, float* SS, bf16_t* HB) {
;     const int lane = threadIdx.x & 63, wave = threadIdx.x >> 6, gw = blockIdx.x * 8 + wave, NGW = gridDim.x * 8;
;     for (int row = row_lo + gw; row < row_hi; row += 2 * NGW) {
;         const int rowb = row + NGW; const bool hasb = rowb < row_hi; const int rb = hasb ? rowb : row;
;         const float* srca = row < NTOK ? src0 + (size_t)row * D : src1 + (size_t)(row - NTOK) * D;
;         const float* srcb = rb < NTOK ? src0 + (size_t)rb * D : src1 + (size_t)(rb - NTOK) * D;
;         const int mba = row < NTOK ? (row >> 12) : 4, mbb = rb < NTOK ? (rb >> 12) : 4;
;         const f32x4* xa = (const f32x4*)srca + lane; const f32x4* xb = (const f32x4*)srcb + lane;
;         f32x4 va[4], vb[4]; float sa = 0.f, sb = 0.f;
; #pragma unroll
;         for (int j = 0; j < 4; ++j) { va[j] = xa[64 * j]; vb[j] = xb[64 * j]; }
.LBB0_402:
	s_or_b64 exec, exec, s[0:1]
	s_cmpk_gt_i32 s82, 0x80
	s_cselect_b32 s34, 0x80, 0
	s_sub_i32 s35, s84, s34
	s_lshl_b32 s35, s35, 3
	v_add_u32_e32 v251, s35, v218
	s_sub_i32 s34, s82, s34
	s_lshl_b32 s34, s34, 3
	s_sub_i32 s35, s34, 0x100000
	s_add_u32 s14, s80, 0x75000
	s_movk_i32 s0, 0x400
	s_addc_u32 s15, s81, 0
	v_cmp_gt_u32_e32 vcc, s0, v251
	s_waitcnt lgkmcnt(0)
	s_barrier
	s_and_saveexec_b64 s[16:17], vcc
	s_cbranch_execz .LBB0_416
	s_sub_u32 s36, s78, s2
	s_subb_u32 s37, s79, s3
	s_mov_b32 s40, 0x400000
	s_mov_b32 s41, 0
	v_mbcnt_hi_u32_b32 v0, -1, v220
	v_and_b32_e32 v1, 64, v0
	v_add_u32_e32 v1, 64, v1
	v_xor_b32_e32 v2, 1, v0
	v_cmp_lt_i32_e32 vcc, v2, v1
	v_mov_b32_e32 v193, 0
	s_mov_b64 s[0:1], 0x1000
	v_cndmask_b32_e32 v2, v0, v2, vcc
	v_lshlrev_b32_e32 v54, 2, v2
	v_xor_b32_e32 v2, 2, v0
	v_cmp_lt_i32_e32 vcc, v2, v1
	v_mov_b32_e32 v195, v193
	s_movk_i32 s20, 0x4000
	v_cndmask_b32_e32 v2, v0, v2, vcc
	v_lshlrev_b32_e32 v55, 2, v2
	v_xor_b32_e32 v2, 4, v0
	v_cmp_lt_i32_e32 vcc, v2, v1
	v_add_u32_e32 v46, 0x4000, v251
	v_lshl_add_u64 v[44:45], s[72:73], 0, v[194:195]
	v_cndmask_b32_e32 v2, v0, v2, vcc
	v_lshlrev_b32_e32 v56, 2, v2
	v_xor_b32_e32 v2, 8, v0
	v_cmp_lt_i32_e32 vcc, v2, v1
	s_ashr_i32 s95, s94, 31
	s_mov_b64 s[18:19], 0
	v_cndmask_b32_e32 v2, v0, v2, vcc
	v_lshlrev_b32_e32 v57, 2, v2
	v_xor_b32_e32 v2, 16, v0
	v_cmp_lt_i32_e32 vcc, v2, v1
	s_movk_i32 s21, 0x4400
	v_mov_b32_e32 v60, s3
	v_cndmask_b32_e32 v2, v0, v2, vcc
	v_lshlrev_b32_e32 v58, 2, v2
	v_xor_b32_e32 v2, 32, v0
	v_cmp_lt_i32_e32 vcc, v2, v1
	v_mov_b32_e32 v61, s2
	s_movk_i32 s22, 0x43ff
	v_cndmask_b32_e32 v0, v0, v2, vcc
	v_lshlrev_b32_e32 v59, 2, v0
	v_lshl_add_u64 v[0:1], s[28:29], 0, v[192:193]
	v_lshl_add_u64 v[40:41], v[0:1], 0, s[0:1]
	v_lshl_add_u64 v[0:1], s[80:81], 0, v[192:193]
	s_mov_b64 s[0:1], 0x4000
	v_cmp_eq_u32_e32 vcc, 0, v178
	v_lshl_add_u64 v[42:43], v[0:1], 0, s[0:1]
	v_lshlrev_b32_e32 v192, 4, v178
	s_branch .LBB0_405
.LBB0_404:
	s_or_b64 exec, exec, s[2:3]
	v_add_u32_e32 v46, s35, v62
	v_cmp_lt_i32_e64 s[0:1], s22, v46
	s_or_b64 s[18:19], s[0:1], s[18:19]
	s_andn2_b64 exec, exec, s[18:19]
	s_cbranch_execz .LBB0_416
.LBB0_405:
	v_add_u32_e32 v0, 0xffffc000, v46
	v_ashrrev_i32_e32 v47, 31, v46
	v_cmp_gt_i32_e64 s[0:1], s20, v46
	v_add_u32_e32 v62, 0x100000, v46
	s_nop 0
	v_cndmask_b32_e64 v1, 0, v47, s[0:1]
	v_cndmask_b32_e64 v0, v0, v46, s[0:1]
	v_cndmask_b32_e64 v3, v60, 0, s[0:1]
	v_cndmask_b32_e64 v2, v61, 0, s[0:1]
	v_lshlrev_b64 v[0:1], 12, v[0:1]
	v_lshl_add_u64 v[0:1], v[2:3], 0, v[0:1]
	v_cmp_gt_i32_e64 s[0:1], s21, v62
	v_lshl_add_u64 v[0:1], v[0:1], 0, v[192:193]
	global_load_dwordx4 v[28:31], v[0:1], off
	v_lshl_add_u64 v[254:255], v[0:1], 0, s[36:37]
	v_cndmask_b32_e64 v48, v46, v62, s[0:1]
	global_load_dwordx4 v[20:23], v[0:1], off offset:1024
	global_load_dwordx4 v[12:15], v[0:1], off offset:2048
	global_load_dwordx4 v[4:7], v[0:1], off offset:3072
	v_add_u32_e32 v0, 0xffffc000, v48
	v_ashrrev_i32_e32 v49, 31, v48
	v_cmp_gt_i32_e64 s[12:13], s20, v48
	s_nop 1
	v_cndmask_b32_e64 v1, 0, v49, s[12:13]
	v_cndmask_b32_e64 v0, v0, v48, s[12:13]
	v_cndmask_b32_e64 v3, v60, 0, s[12:13]
	v_cndmask_b32_e64 v2, v61, 0, s[12:13]
	v_lshlrev_b64 v[0:1], 12, v[0:1]
	v_lshl_add_u64 v[0:1], v[2:3], 0, v[0:1]
	v_lshl_add_u64 v[0:1], v[0:1], 0, v[192:193]
	global_load_dwordx4 v[24:27], v[0:1], off
	global_load_dwordx4 v[16:19], v[0:1], off offset:1024
	global_load_dwordx4 v[8:11], v[0:1], off offset:2048
	s_nop 0
	global_load_dwordx4 v[0:3], v[0:1], off offset:3072
	s_movk_i32 s38, 11
	s_waitcnt vmcnt(0)
; __device__ __forceinline__ void prenorm_rows(const float* src0, const float* src1, int row_lo, int row_hi, const float* g, const float* scale, float* SS, bf16_t* HB) {
;     ...
;         for (int j = 0; j < 4; ++j) { va[j] = xa[64 * j]; vb[j] = xb[64 * j]; }
; #pragma unroll
;         for (int j = 0; j < 4; ++j) { sa += (va[j][0] * va[j][0] + va[j][1] * va[j][1]) + (va[j][2] * va[j][2] + va[j][3] * va[j][3]); sb += (vb[j][0] * vb[j][0] + vb[j][1] * vb[j][1]) + (vb[j][2] * vb[j][2] + vb[j][3] * vb[j][3]); }
;         sa = wave_sum(sa); sb = wave_sum(sb);
;         if (lane == 0) { SS[row] = sa; if (hasb) SS[rowb] = sb; }
.Lctx_acc_loop:
	global_load_dwordx4 v[232:235], v[254:255], off
	global_load_dwordx4 v[236:239], v[254:255], off offset:1024
	global_load_dwordx4 v[240:243], v[254:255], off offset:2048
	global_load_dwordx4 v[244:247], v[254:255], off offset:3072
	v_lshl_add_u64 v[254:255], v[254:255], 0, s[40:41]
	s_sub_i32 s38, s38, 1
	s_cmp_lg_u32 s38, 0
	s_waitcnt vmcnt(0)
	v_pk_add_f32 v[28:29], v[28:29], v[232:233]
	v_pk_add_f32 v[30:31], v[30:31], v[234:235]
	v_pk_add_f32 v[20:21], v[20:21], v[236:237]
	v_pk_add_f32 v[22:23], v[22:23], v[238:239]
	v_pk_add_f32 v[12:13], v[12:13], v[240:241]
	v_pk_add_f32 v[14:15], v[14:15], v[242:243]
	v_pk_add_f32 v[4:5], v[4:5], v[244:245]
	v_pk_add_f32 v[6:7], v[6:7], v[246:247]
	s_cbranch_scc1 .Lctx_acc_loop
	v_mul_f32_e32 v32, v29, v29
	v_mul_f32_e32 v33, v31, v31
	s_waitcnt vmcnt(6)
	v_mul_f32_e32 v34, v21, v21
	v_mul_f32_e32 v35, v23, v23
	s_waitcnt vmcnt(5)
	v_mul_f32_e32 v36, v13, v13
	v_mul_f32_e32 v37, v15, v15
	v_fmac_f32_e32 v32, v28, v28
	v_fmac_f32_e32 v33, v30, v30
	v_fmac_f32_e32 v34, v20, v20
	v_fmac_f32_e32 v35, v22, v22
	s_waitcnt vmcnt(4)
	v_mul_f32_e32 v38, v5, v5
	v_mul_f32_e32 v39, v7, v7
	v_fmac_f32_e32 v36, v12, v12
	v_fmac_f32_e32 v37, v14, v14
	v_add_f32_e32 v32, v32, v33
	v_add_f32_e32 v34, v34, v35
	v_fmac_f32_e32 v38, v4, v4
	v_fmac_f32_e32 v39, v6, v6
	v_add_f32_e32 v36, v36, v37
	v_add_f32_e32 v38, v38, v39
	v_add_f32_e32 v32, v32, v34
	v_add_f32_e32 v32, v32, v36
	v_add_f32_e32 v32, v32, v38
	s_waitcnt vmcnt(3)
	v_mul_f32_e32 v33, v25, v25
	v_mul_f32_e32 v50, v27, v27
	s_waitcnt vmcnt(2)
	v_mul_f32_e32 v35, v17, v17
	v_mul_f32_e32 v51, v19, v19
	s_waitcnt vmcnt(1)
	v_mul_f32_e32 v37, v9, v9
	v_mul_f32_e32 v52, v11, v11
	v_fmac_f32_e32 v33, v24, v24
	v_fmac_f32_e32 v50, v26, v26
	v_fmac_f32_e32 v35, v16, v16
	v_fmac_f32_e32 v51, v18, v18
	s_waitcnt vmcnt(0)
	v_mul_f32_e32 v39, v1, v1
	v_mul_f32_e32 v53, v3, v3
	v_fmac_f32_e32 v37, v8, v8
	v_fmac_f32_e32 v52, v10, v10
	v_add_f32_e32 v33, v33, v50
	v_add_f32_e32 v34, v35, v51
	v_fmac_f32_e32 v39, v0, v0
	v_fmac_f32_e32 v53, v2, v2
	v_add_f32_e32 v35, v37, v52
	v_add_f32_e32 v33, v33, v34
	v_add_f32_e32 v36, v39, v53
	v_add_f32_e32 v33, v33, v35
	v_add_f32_e32 v33, v33, v36
	ds_bpermute_b32 v34, v54, v32
	ds_bpermute_b32 v35, v54, v33
	s_waitcnt lgkmcnt(1)
	v_add_f32_e32 v32, v32, v34
	s_waitcnt lgkmcnt(0)
	v_add_f32_e32 v33, v33, v35
	ds_bpermute_b32 v34, v55, v32
	ds_bpermute_b32 v35, v55, v33
	s_waitcnt lgkmcnt(1)
	v_add_f32_e32 v32, v32, v34
	s_waitcnt lgkmcnt(0)
	v_add_f32_e32 v33, v33, v35
	ds_bpermute_b32 v34, v56, v32
	ds_bpermute_b32 v35, v56, v33
	s_waitcnt lgkmcnt(1)
	v_add_f32_e32 v32, v32, v34
	s_waitcnt lgkmcnt(0)
	v_add_f32_e32 v33, v33, v35
	ds_bpermute_b32 v34, v57, v32
	ds_bpermute_b32 v35, v57, v33
	s_waitcnt lgkmcnt(1)
	v_add_f32_e32 v32, v32, v34
	s_waitcnt lgkmcnt(0)
	v_add_f32_e32 v35, v33, v35
	ds_bpermute_b32 v34, v58, v32
	ds_bpermute_b32 v36, v58, v35
	s_waitcnt lgkmcnt(1)
	v_add_f32_e32 v32, v32, v34
	s_waitcnt lgkmcnt(0)
	v_add_f32_e32 v34, v35, v36
	ds_bpermute_b32 v33, v59, v32
	ds_bpermute_b32 v35, v59, v34
	s_and_saveexec_b64 s[2:3], vcc
	s_cbranch_execz .LBB0_408
	s_waitcnt lgkmcnt(1)
	v_add_f32_e32 v36, v32, v33
	v_lshl_add_u64 v[32:33], v[46:47], 2, s[14:15]
	global_store_dword v[32:33], v36, off
	s_and_b64 exec, exec, s[0:1]
	s_cbranch_execz .LBB0_408
	s_waitcnt lgkmcnt(0)
	v_add_f32_e32 v34, v34, v35
	v_lshl_add_u64 v[32:33], s[94:95], 2, v[32:33]
	global_store_dword v[32:33], v34, off
